# rwkv/ssd chunk loops: arrive at the per-chunk half barrier once all LDS reads of the chunk are issued (step 14), wait at the chunk end
# speedup vs baseline: 1.0056x; 1.0044x over previous
; __device__ __forceinline__ void ssd_scan_unit(CP p, int l, int u, char* smem) {
;     ...
;     for (int s = 0; s < 16; ++s) {
;       const float* sb = cb + (s + 1) * SST;
;       const float4 B0n = *reinterpret_cast<const float4*>(sb + j * 4), B1n = *reinterpret_cast<const float4*>(sb + 64 + j * 4);
;       const float4 C0n = *reinterpret_cast<const float4*>(sb + 128 + j * 4), C1n = *reinterpret_cast<const float4*>(sb + 192 + j * 4);
;       const float xdtn = sb[256 + prow], xrn = sb[272 + prow], an = sb[288];
;       __builtin_amdgcn_sched_barrier(0);
;       hs[0] = fmaf(a, hs[0], xdt * B0.x); hs[1] = fmaf(a, hs[1], xdt * B0.y); hs[2] = fmaf(a, hs[2], xdt * B0.z); hs[3] = fmaf(a, hs[3], xdt * B0.w);
;       hs[4] = fmaf(a, hs[4], xdt * B1.x); hs[5] = fmaf(a, hs[5], xdt * B1.y); hs[6] = fmaf(a, hs[6], xdt * B1.z); hs[7] = fmaf(a, hs[7], xdt * B1.w);
;       float y = hs[0] * C0.x + hs[1] * C0.y + hs[2] * C0.z + hs[3] * C0.w + hs[4] * C1.x + hs[5] * C1.y + hs[6] * C1.z + hs[7] * C1.w;
;       y = allreduce16(y);
;       y = fmaf(Dh, xr, y);
;       if (j == s) ykeep = y;
;       B0 = B0n; B1 = B1n; C0 = C0n; C1 = C1n; xdt = xdtn; xr = xrn; a = an;
;     }
.Lsd_skipgl:
	s_waitcnt lgkmcnt(13)
	v_pk_fma_f32 v[32:33], v[134:135], v[32:33], v[176:177]
	v_pk_fma_f32 v[38:39], v[134:135], v[38:39], v[178:179]
	v_pk_fma_f32 v[36:37], v[134:135], v[36:37], v[180:181]
	v_pk_fma_f32 v[34:35], v[134:135], v[34:35], v[182:183]
	v_pk_mul_f32 v[184:185], v[32:33], v[98:99]
	v_pk_mul_f32 v[176:177], v[112:113], v[108:109]
	v_pk_fma_f32 v[184:185], v[38:39], v[100:101], v[184:185]
	v_pk_mul_f32 v[178:179], v[114:115], v[108:109]
	v_pk_fma_f32 v[184:185], v[36:37], v[102:103], v[184:185]
	v_pk_mul_f32 v[180:181], v[116:117], v[108:109]
	v_pk_fma_f32 v[184:185], v[34:35], v[104:105], v[184:185]
	v_pk_mul_f32 v[182:183], v[118:119], v[108:109]
	v_add_f32_e32 v168, v184, v185
	ds_read_b128 v[112:115], v84 offset:13024
	ds_read_b128 v[116:119], v84 offset:13280
	ds_read_b128 v[98:101], v84 offset:12352
	ds_read_b128 v[102:105], v84 offset:12608
	ds_read_b128 v[106:109], v85 offset:1120
	s_waitcnt lgkmcnt(13)
	v_pk_fma_f32 v[32:33], v[136:137], v[32:33], v[176:177]
	v_pk_fma_f32 v[38:39], v[136:137], v[38:39], v[178:179]
	v_pk_fma_f32 v[36:37], v[136:137], v[36:37], v[180:181]
	v_pk_fma_f32 v[34:35], v[136:137], v[34:35], v[182:183]
	v_pk_mul_f32 v[184:185], v[32:33], v[120:121]
	v_pk_mul_f32 v[176:177], v[90:91], v[128:129]
	v_pk_fma_f32 v[184:185], v[38:39], v[122:123], v[184:185]
	v_pk_mul_f32 v[178:179], v[92:93], v[128:129]
	v_pk_fma_f32 v[184:185], v[36:37], v[124:125], v[184:185]
	v_pk_mul_f32 v[180:181], v[94:95], v[128:129]
	v_pk_fma_f32 v[184:185], v[34:35], v[126:127], v[184:185]
	v_pk_mul_f32 v[182:183], v[96:97], v[128:129]
	v_add_f32_e32 v169, v184, v185
	ds_read_b128 v[90:93], v84 offset:14208
	ds_read_b128 v[94:97], v84 offset:14464
	ds_read_b128 v[120:123], v84 offset:13536
	ds_read_b128 v[124:127], v84 offset:13792
	ds_read_b128 v[134:137], v86 offset:37984
	s_waitcnt lgkmcnt(6)
	v_pk_fma_f32 v[32:33], v[138:139], v[32:33], v[176:177]
	v_pk_fma_f32 v[38:39], v[138:139], v[38:39], v[178:179]
	v_pk_fma_f32 v[36:37], v[138:139], v[36:37], v[180:181]
	v_pk_fma_f32 v[34:35], v[138:139], v[34:35], v[182:183]
	v_pk_mul_f32 v[184:185], v[32:33], v[98:99]
	v_pk_mul_f32 v[176:177], v[112:113], v[130:131]
	v_pk_fma_f32 v[184:185], v[38:39], v[100:101], v[184:185]
	v_pk_mul_f32 v[178:179], v[114:115], v[130:131]
	v_pk_fma_f32 v[184:185], v[36:37], v[102:103], v[184:185]
	v_pk_mul_f32 v[180:181], v[116:117], v[130:131]
	v_pk_fma_f32 v[184:185], v[34:35], v[104:105], v[184:185]
	v_pk_mul_f32 v[182:183], v[118:119], v[130:131]
	v_add_f32_e32 v170, v184, v185
	ds_read_b128 v[112:115], v84 offset:15392
	ds_read_b128 v[116:119], v84 offset:15648
	ds_read_b128 v[98:101], v84 offset:14720
	ds_read_b128 v[102:105], v84 offset:14976
	ds_read_b128 v[128:131], v85 offset:1136
	s_waitcnt lgkmcnt(6)
	v_pk_fma_f32 v[32:33], v[140:141], v[32:33], v[176:177]
	v_pk_fma_f32 v[38:39], v[140:141], v[38:39], v[178:179]
	v_pk_fma_f32 v[36:37], v[140:141], v[36:37], v[180:181]
	v_pk_fma_f32 v[34:35], v[140:141], v[34:35], v[182:183]
	v_pk_mul_f32 v[184:185], v[32:33], v[120:121]
	v_pk_mul_f32 v[176:177], v[90:91], v[106:107]
	v_pk_fma_f32 v[184:185], v[38:39], v[122:123], v[184:185]
	v_pk_mul_f32 v[178:179], v[92:93], v[106:107]
	v_pk_fma_f32 v[184:185], v[36:37], v[124:125], v[184:185]
	v_pk_mul_f32 v[180:181], v[94:95], v[106:107]
	v_pk_fma_f32 v[184:185], v[34:35], v[126:127], v[184:185]
	v_pk_mul_f32 v[182:183], v[96:97], v[106:107]
	v_add_f32_e32 v171, v184, v185
	ds_read_b128 v[90:93], v84 offset:16576
	ds_read_b128 v[94:97], v84 offset:16832
	ds_read_b128 v[120:123], v84 offset:15904
	ds_read_b128 v[124:127], v84 offset:16160
	ds_read_b128 v[138:141], v86 offset:38000
	s_waitcnt lgkmcnt(6)
	v_pk_fma_f32 v[32:33], v[134:135], v[32:33], v[176:177]
	v_pk_fma_f32 v[38:39], v[134:135], v[38:39], v[178:179]
	v_pk_fma_f32 v[36:37], v[134:135], v[36:37], v[180:181]
	v_pk_fma_f32 v[34:35], v[134:135], v[34:35], v[182:183]
	v_pk_mul_f32 v[184:185], v[32:33], v[98:99]
	v_pk_mul_f32 v[176:177], v[112:113], v[108:109]
	v_pk_fma_f32 v[184:185], v[38:39], v[100:101], v[184:185]
	v_pk_mul_f32 v[178:179], v[114:115], v[108:109]
	v_pk_fma_f32 v[184:185], v[36:37], v[102:103], v[184:185]
	v_pk_mul_f32 v[180:181], v[116:117], v[108:109]
	v_pk_fma_f32 v[184:185], v[34:35], v[104:105], v[184:185]
	v_pk_mul_f32 v[182:183], v[118:119], v[108:109]
	v_add_f32_e32 v172, v184, v185
	ds_read_b128 v[112:115], v84 offset:17760
	ds_read_b128 v[116:119], v84 offset:18016
	ds_read_b128 v[98:101], v84 offset:17088
	ds_read_b128 v[102:105], v84 offset:17344
	s_waitcnt lgkmcnt(5)
; __device__ __forceinline__ bf16_t f2bf(float f) { return (bf16_t)(pack2(f, 0.f) & 0xffffu); }
; __device__ __forceinline__ void ssd_scan_unit(CP p, int l, int u, char* smem) {
;     ...
;       hs[0] = fmaf(a, hs[0], xdt * B0.x); hs[1] = fmaf(a, hs[1], xdt * B0.y); hs[2] = fmaf(a, hs[2], xdt * B0.z); hs[3] = fmaf(a, hs[3], xdt * B0.w);
;       hs[4] = fmaf(a, hs[4], xdt * B1.x); hs[5] = fmaf(a, hs[5], xdt * B1.y); hs[6] = fmaf(a, hs[6], xdt * B1.z); hs[7] = fmaf(a, hs[7], xdt * B1.w);
;       float y = hs[0] * C0.x + hs[1] * C0.y + hs[2] * C0.z + hs[3] * C0.w + hs[4] * C1.x + hs[5] * C1.y + hs[6] * C1.z + hs[7] * C1.w;
;       y = allreduce16(y);
;       y = fmaf(Dh, xr, y);
;       if (j == s) ykeep = y;
;       B0 = B0n; B1 = B1n; C0 = C0n; C1 = C1n; xdt = xdtn; xr = xrn; a = an;
;     }
;     Y[(size_t)(rowof(b, c * 16) + j) * 1024 + h * 64 + q * 16 + prow] = f2bf(ykeep);
;     if (c + 1 < NCH) lwrite((c + 1) & 1);
;     half_barrier(smem);
	v_pk_fma_f32 v[32:33], v[136:137], v[32:33], v[176:177]
	v_pk_fma_f32 v[38:39], v[136:137], v[38:39], v[178:179]
	v_pk_fma_f32 v[36:37], v[136:137], v[36:37], v[180:181]
	v_pk_fma_f32 v[34:35], v[136:137], v[34:35], v[182:183]
	v_pk_mul_f32 v[184:185], v[32:33], v[120:121]
	v_pk_mul_f32 v[176:177], v[90:91], v[128:129]
	v_pk_fma_f32 v[184:185], v[38:39], v[122:123], v[184:185]
	v_pk_mul_f32 v[178:179], v[92:93], v[128:129]
	v_pk_fma_f32 v[184:185], v[36:37], v[124:125], v[184:185]
	v_pk_mul_f32 v[180:181], v[94:95], v[128:129]
	v_pk_fma_f32 v[184:185], v[34:35], v[126:127], v[184:185]
	v_pk_mul_f32 v[182:183], v[96:97], v[128:129]
	v_add_f32_e32 v173, v184, v185
	ds_read_b128 v[120:123], v84 offset:18272
	ds_read_b128 v[124:127], v84 offset:18528
	s_mov_b64 s[12:13], exec
	s_mov_b64 exec, 1
	ds_add_u32 v193, v195 offset:8
	s_mov_b64 exec, s[12:13]
	v_add_u32_e32 v194, 4, v194
	s_waitcnt lgkmcnt(3)
	v_pk_fma_f32 v[32:33], v[138:139], v[32:33], v[176:177]
	v_pk_fma_f32 v[38:39], v[138:139], v[38:39], v[178:179]
	v_pk_fma_f32 v[36:37], v[138:139], v[36:37], v[180:181]
	v_pk_fma_f32 v[34:35], v[138:139], v[34:35], v[182:183]
	v_pk_mul_f32 v[184:185], v[32:33], v[98:99]
	v_pk_mul_f32 v[176:177], v[112:113], v[130:131]
	v_pk_fma_f32 v[184:185], v[38:39], v[100:101], v[184:185]
	v_pk_mul_f32 v[178:179], v[114:115], v[130:131]
	v_pk_fma_f32 v[184:185], v[36:37], v[102:103], v[184:185]
	v_pk_mul_f32 v[180:181], v[116:117], v[130:131]
	v_pk_fma_f32 v[184:185], v[34:35], v[104:105], v[184:185]
	v_pk_mul_f32 v[182:183], v[118:119], v[130:131]
	v_add_f32_e32 v174, v184, v185
	s_waitcnt lgkmcnt(1)
	v_pk_fma_f32 v[32:33], v[140:141], v[32:33], v[176:177]
	v_pk_fma_f32 v[38:39], v[140:141], v[38:39], v[178:179]
	v_pk_fma_f32 v[36:37], v[140:141], v[36:37], v[180:181]
	v_pk_fma_f32 v[34:35], v[140:141], v[34:35], v[182:183]
	v_pk_mul_f32 v[184:185], v[32:33], v[120:121]
	v_pk_fma_f32 v[184:185], v[38:39], v[122:123], v[184:185]
	v_pk_fma_f32 v[184:185], v[36:37], v[124:125], v[184:185]
	v_pk_fma_f32 v[184:185], v[34:35], v[126:127], v[184:185]
	v_add_f32_e32 v175, v184, v185
	v_add_f32_dpp v160, v160, v160 row_ror:8 row_mask:0xf bank_mask:0x3 bound_ctrl:1
	v_add_f32_dpp v161, v161, v161 row_ror:8 row_mask:0xf bank_mask:0x3 bound_ctrl:1
	v_add_f32_dpp v162, v162, v162 row_ror:8 row_mask:0xf bank_mask:0x3 bound_ctrl:1
	v_add_f32_dpp v163, v163, v163 row_ror:8 row_mask:0xf bank_mask:0x3 bound_ctrl:1
	v_add_f32_dpp v164, v164, v164 row_ror:8 row_mask:0xf bank_mask:0x3 bound_ctrl:1
	v_add_f32_dpp v165, v165, v165 row_ror:8 row_mask:0xf bank_mask:0x3 bound_ctrl:1
	v_add_f32_dpp v166, v166, v166 row_ror:8 row_mask:0xf bank_mask:0x3 bound_ctrl:1
	v_add_f32_dpp v167, v167, v167 row_ror:8 row_mask:0xf bank_mask:0x3 bound_ctrl:1
	v_add_f32_dpp v160, v168, v168 row_ror:8 row_mask:0xf bank_mask:0xc bound_ctrl:1
	v_add_f32_dpp v161, v169, v169 row_ror:8 row_mask:0xf bank_mask:0xc bound_ctrl:1
	v_add_f32_dpp v162, v170, v170 row_ror:8 row_mask:0xf bank_mask:0xc bound_ctrl:1
	v_add_f32_dpp v163, v171, v171 row_ror:8 row_mask:0xf bank_mask:0xc bound_ctrl:1
	v_add_f32_dpp v164, v172, v172 row_ror:8 row_mask:0xf bank_mask:0xc bound_ctrl:1
	v_add_f32_dpp v165, v173, v173 row_ror:8 row_mask:0xf bank_mask:0xc bound_ctrl:1
	v_add_f32_dpp v166, v174, v174 row_ror:8 row_mask:0xf bank_mask:0xc bound_ctrl:1
	v_add_f32_dpp v167, v175, v175 row_ror:8 row_mask:0xf bank_mask:0xc bound_ctrl:1
	v_add_f32_dpp v160, v160, v160 row_half_mirror row_mask:0xf bank_mask:0x5 bound_ctrl:1
	v_add_f32_dpp v161, v161, v161 row_half_mirror row_mask:0xf bank_mask:0x5 bound_ctrl:1
	v_add_f32_dpp v162, v162, v162 row_half_mirror row_mask:0xf bank_mask:0x5 bound_ctrl:1
	v_add_f32_dpp v163, v163, v163 row_half_mirror row_mask:0xf bank_mask:0x5 bound_ctrl:1
	v_add_f32_dpp v160, v164, v164 row_half_mirror row_mask:0xf bank_mask:0xa bound_ctrl:1
	v_add_f32_dpp v161, v165, v165 row_half_mirror row_mask:0xf bank_mask:0xa bound_ctrl:1
	v_add_f32_dpp v162, v166, v166 row_half_mirror row_mask:0xf bank_mask:0xa bound_ctrl:1
	v_add_f32_dpp v163, v167, v167 row_half_mirror row_mask:0xf bank_mask:0xa bound_ctrl:1
	v_and_b32_e32 v188, 2, v44
	v_cmp_ne_u32_e32 vcc, 0, v188
	v_and_b32_e32 v188, 1, v44
	s_nop 0
	v_cndmask_b32_e32 v189, v160, v162, vcc
	v_cndmask_b32_e32 v190, v162, v160, vcc
	v_cndmask_b32_e32 v191, v161, v163, vcc
	v_cndmask_b32_e32 v192, v163, v161, vcc
	v_cmp_ne_u32_e32 vcc, 0, v188
	v_add_f32_dpp v160, v190, v189 quad_perm:[2,3,0,1] row_mask:0xf bank_mask:0xf bound_ctrl:1
	v_add_f32_dpp v161, v192, v191 quad_perm:[2,3,0,1] row_mask:0xf bank_mask:0xf bound_ctrl:1
	v_cndmask_b32_e32 v189, v160, v161, vcc
	v_cndmask_b32_e32 v190, v161, v160, vcc
	s_nop 1
	v_add_f32_dpp v187, v190, v189 quad_perm:[1,0,3,2] row_mask:0xf bank_mask:0xf bound_ctrl:1
	v_fma_f32 v60, v43, v186, v187
	s_lshl_b32 s5, s4, 4
	s_add_i32 s5, s5, s11
	s_cmp_eq_u32 s4, 0
	s_cselect_b32 s5, s10, s5
	v_or_b32_e32 v8, s5, v44
	v_ashrrev_i32_e32 v9, 31, v8
	v_lshlrev_b64 v[8:9], 11, v[8:9]
	v_cvt_pk_bf16_f32 v10, v60, s0
	v_lshl_add_u64 v[8:9], v[28:29], 0, v[8:9]
	global_store_short v[8:9], v10, off
	s_waitcnt lgkmcnt(0)

; __device__ __forceinline__ void rwkv_scan_unit(CP p, int u, char* smem) {
;     ...
;     for (int s = 0; s < 16; ++s) {
;       const float* sb = cb + (s + 1) * 384;
;       const float4 om_n = *reinterpret_cast<const float4*>(sb + j * 4);
;       const float4 kk_n = *reinterpret_cast<const float4*>(sb + 64 + j * 4);
;       const float4 bb_n = *reinterpret_cast<const float4*>(sb + 128 + j * 4);
;       const float4 kp_n = *reinterpret_cast<const float4*>(sb + 192 + j * 4);
;       const float4 rr_n = *reinterpret_cast<const float4*>(sb + 256 + j * 4);
;       const float vv_n = sb[320 + rowv];
;       __builtin_amdgcn_sched_barrier(0);
;       float d = s0 * kk.x + s1 * kk.y + s2 * kk.z + s3 * kk.w;
;       d = allreduce16(d);
;       const float sa = -d;
;       s0 = fmaf(-s0, om.x, s0); s1 = fmaf(-s1, om.y, s1); s2 = fmaf(-s2, om.z, s2); s3 = fmaf(-s3, om.w, s3);
;       s0 = fmaf(sa, bb.x, s0); s1 = fmaf(sa, bb.y, s1); s2 = fmaf(sa, bb.z, s2); s3 = fmaf(sa, bb.w, s3);
;       s0 = fmaf(vv, kp.x, s0); s1 = fmaf(vv, kp.y, s1); s2 = fmaf(vv, kp.z, s2); s3 = fmaf(vv, kp.w, s3);
;       float y = s0 * rr.x + s1 * rr.y + s2 * rr.z + s3 * rr.w;
;       y = allreduce16(y);
;       if (j == s) ykeep = y;
;       om = om_n; kk = kk_n; bb = bb_n; kp = kp_n; rr = rr_n; vv = vv_n;
;     }
.Lrw_skipgl:
	s_waitcnt lgkmcnt(13)
	v_pk_mul_f32 v[176:177], v[60:61], v[138:139]
	v_pk_fma_f32 v[176:177], v[58:59], v[140:141], v[176:177]
	ds_read_b128 v[116:119], v78 offset:15616
	ds_read_b128 v[112:115], v78 offset:15360
	v_pk_fma_f32 v[180:181], v[60:61], v[134:135], v[60:61] neg_lo:[1,0,0] neg_hi:[1,0,0]
	v_add_f32_e32 v178, v176, v177
	v_pk_fma_f32 v[182:183], v[58:59], v[136:137], v[58:59] neg_lo:[1,0,0] neg_hi:[1,0,0]
	ds_read_b128 v[124:127], v78 offset:16128
	v_add_f32_dpp v178, v178, v178 quad_perm:[1,0,3,2] row_mask:0xf bank_mask:0xf bound_ctrl:1
	v_pk_fma_f32 v[180:181], v[146:147], v[152:153], v[180:181] op_sel_hi:[0,1,1]
	v_pk_fma_f32 v[182:183], v[146:147], v[154:155], v[182:183] op_sel_hi:[0,1,1]
	v_add_f32_dpp v178, v178, v178 quad_perm:[2,3,0,1] row_mask:0xf bank_mask:0xf bound_ctrl:1
	v_pk_mul_f32 v[184:185], v[60:61], v[128:129]
	v_pk_fma_f32 v[184:185], v[58:59], v[130:131], v[184:185]
	v_add_f32_dpp v178, v178, v178 row_half_mirror row_mask:0xf bank_mask:0xf bound_ctrl:1
	v_add_f32_e32 v167, v184, v185
	ds_read_b32 v132, v79 offset:16640
	v_add_f32_dpp v178, v178, v178 row_mirror row_mask:0xf bank_mask:0xf bound_ctrl:1
	ds_read_b128 v[120:123], v78 offset:15872
	ds_read_b128 v[128:131], v78 offset:16384
	v_pk_fma_f32 v[60:61], v[178:179], v[142:143], v[180:181] op_sel_hi:[0,1,1] neg_lo:[1,0,0] neg_hi:[1,0,0]
	v_pk_fma_f32 v[58:59], v[178:179], v[144:145], v[182:183] op_sel_hi:[0,1,1] neg_lo:[1,0,0] neg_hi:[1,0,0]
	s_waitcnt lgkmcnt(13)
	v_pk_mul_f32 v[176:177], v[60:61], v[94:95]
	v_pk_fma_f32 v[176:177], v[58:59], v[96:97], v[176:177]
	ds_read_b128 v[138:141], v78 offset:17152
	ds_read_b128 v[134:137], v78 offset:16896
	v_pk_fma_f32 v[180:181], v[60:61], v[90:91], v[60:61] neg_lo:[1,0,0] neg_hi:[1,0,0]
	v_add_f32_e32 v178, v176, v177
	v_pk_fma_f32 v[182:183], v[58:59], v[92:93], v[58:59] neg_lo:[1,0,0] neg_hi:[1,0,0]
	ds_read_b128 v[152:155], v78 offset:17664
	v_add_f32_dpp v178, v178, v178 quad_perm:[1,0,3,2] row_mask:0xf bank_mask:0xf bound_ctrl:1
	v_pk_fma_f32 v[180:181], v[110:111], v[102:103], v[180:181] op_sel_hi:[0,1,1]
	v_pk_fma_f32 v[182:183], v[110:111], v[104:105], v[182:183] op_sel_hi:[0,1,1]
	v_add_f32_dpp v178, v178, v178 quad_perm:[2,3,0,1] row_mask:0xf bank_mask:0xf bound_ctrl:1
	v_pk_mul_f32 v[184:185], v[60:61], v[156:157]
	v_pk_fma_f32 v[184:185], v[58:59], v[158:159], v[184:185]
	v_add_f32_dpp v178, v178, v178 row_half_mirror row_mask:0xf bank_mask:0xf bound_ctrl:1
	v_add_f32_e32 v168, v184, v185
	ds_read_b32 v146, v79 offset:18176
	v_add_f32_dpp v178, v178, v178 row_mirror row_mask:0xf bank_mask:0xf bound_ctrl:1
	ds_read_b128 v[142:145], v78 offset:17408
	ds_read_b128 v[156:159], v78 offset:17920
	v_pk_fma_f32 v[60:61], v[178:179], v[98:99], v[180:181] op_sel_hi:[0,1,1] neg_lo:[1,0,0] neg_hi:[1,0,0]
	v_pk_fma_f32 v[58:59], v[178:179], v[100:101], v[182:183] op_sel_hi:[0,1,1] neg_lo:[1,0,0] neg_hi:[1,0,0]
	s_waitcnt lgkmcnt(7)
	v_pk_mul_f32 v[176:177], v[60:61], v[116:117]
	v_pk_fma_f32 v[176:177], v[58:59], v[118:119], v[176:177]
	ds_read_b128 v[94:97], v78 offset:18688
	ds_read_b128 v[90:93], v78 offset:18432
	v_pk_fma_f32 v[180:181], v[60:61], v[112:113], v[60:61] neg_lo:[1,0,0] neg_hi:[1,0,0]
	v_add_f32_e32 v178, v176, v177
	v_pk_fma_f32 v[182:183], v[58:59], v[114:115], v[58:59] neg_lo:[1,0,0] neg_hi:[1,0,0]
	ds_read_b128 v[102:105], v78 offset:19200
	v_add_f32_dpp v178, v178, v178 quad_perm:[1,0,3,2] row_mask:0xf bank_mask:0xf bound_ctrl:1
	v_pk_fma_f32 v[180:181], v[132:133], v[124:125], v[180:181] op_sel_hi:[0,1,1]
	v_pk_fma_f32 v[182:183], v[132:133], v[126:127], v[182:183] op_sel_hi:[0,1,1]
	v_add_f32_dpp v178, v178, v178 quad_perm:[2,3,0,1] row_mask:0xf bank_mask:0xf bound_ctrl:1
	v_pk_mul_f32 v[184:185], v[60:61], v[106:107]
	v_pk_fma_f32 v[184:185], v[58:59], v[108:109], v[184:185]
	v_add_f32_dpp v178, v178, v178 row_half_mirror row_mask:0xf bank_mask:0xf bound_ctrl:1
	v_add_f32_e32 v169, v184, v185
	ds_read_b32 v110, v79 offset:19712
	v_add_f32_dpp v178, v178, v178 row_mirror row_mask:0xf bank_mask:0xf bound_ctrl:1
	ds_read_b128 v[98:101], v78 offset:18944
	ds_read_b128 v[106:109], v78 offset:19456
	v_pk_fma_f32 v[60:61], v[178:179], v[120:121], v[180:181] op_sel_hi:[0,1,1] neg_lo:[1,0,0] neg_hi:[1,0,0]
	v_pk_fma_f32 v[58:59], v[178:179], v[122:123], v[182:183] op_sel_hi:[0,1,1] neg_lo:[1,0,0] neg_hi:[1,0,0]
	s_waitcnt lgkmcnt(7)
	v_pk_mul_f32 v[176:177], v[60:61], v[138:139]
	v_pk_fma_f32 v[176:177], v[58:59], v[140:141], v[176:177]
	ds_read_b128 v[116:119], v78 offset:20224
	ds_read_b128 v[112:115], v78 offset:19968
	v_pk_fma_f32 v[180:181], v[60:61], v[134:135], v[60:61] neg_lo:[1,0,0] neg_hi:[1,0,0]
	v_add_f32_e32 v178, v176, v177
	v_pk_fma_f32 v[182:183], v[58:59], v[136:137], v[58:59] neg_lo:[1,0,0] neg_hi:[1,0,0]
	ds_read_b128 v[124:127], v78 offset:20736
	v_add_f32_dpp v178, v178, v178 quad_perm:[1,0,3,2] row_mask:0xf bank_mask:0xf bound_ctrl:1
	v_pk_fma_f32 v[180:181], v[146:147], v[152:153], v[180:181] op_sel_hi:[0,1,1]
	v_pk_fma_f32 v[182:183], v[146:147], v[154:155], v[182:183] op_sel_hi:[0,1,1]
	v_add_f32_dpp v178, v178, v178 quad_perm:[2,3,0,1] row_mask:0xf bank_mask:0xf bound_ctrl:1
	v_pk_mul_f32 v[184:185], v[60:61], v[128:129]
	v_pk_fma_f32 v[184:185], v[58:59], v[130:131], v[184:185]
	v_add_f32_dpp v178, v178, v178 row_half_mirror row_mask:0xf bank_mask:0xf bound_ctrl:1
	v_add_f32_e32 v170, v184, v185
	ds_read_b32 v132, v79 offset:21248
	v_add_f32_dpp v178, v178, v178 row_mirror row_mask:0xf bank_mask:0xf bound_ctrl:1
	ds_read_b128 v[120:123], v78 offset:20480
	ds_read_b128 v[128:131], v78 offset:20992
	v_pk_fma_f32 v[60:61], v[178:179], v[142:143], v[180:181] op_sel_hi:[0,1,1] neg_lo:[1,0,0] neg_hi:[1,0,0]
	v_pk_fma_f32 v[58:59], v[178:179], v[144:145], v[182:183] op_sel_hi:[0,1,1] neg_lo:[1,0,0] neg_hi:[1,0,0]
	s_waitcnt lgkmcnt(7)
; __device__ __forceinline__ void rwkv_scan_unit(CP p, int u, char* smem) {
;     ...
;     for (int s = 0; s < 16; ++s) {
;       const float* sb = cb + (s + 1) * 384;
;       const float4 om_n = *reinterpret_cast<const float4*>(sb + j * 4);
;       const float4 kk_n = *reinterpret_cast<const float4*>(sb + 64 + j * 4);
;       const float4 bb_n = *reinterpret_cast<const float4*>(sb + 128 + j * 4);
;       const float4 kp_n = *reinterpret_cast<const float4*>(sb + 192 + j * 4);
;       const float4 rr_n = *reinterpret_cast<const float4*>(sb + 256 + j * 4);
;       const float vv_n = sb[320 + rowv];
;       __builtin_amdgcn_sched_barrier(0);
;       float d = s0 * kk.x + s1 * kk.y + s2 * kk.z + s3 * kk.w;
;       d = allreduce16(d);
;       const float sa = -d;
;       s0 = fmaf(-s0, om.x, s0); s1 = fmaf(-s1, om.y, s1); s2 = fmaf(-s2, om.z, s2); s3 = fmaf(-s3, om.w, s3);
;       s0 = fmaf(sa, bb.x, s0); s1 = fmaf(sa, bb.y, s1); s2 = fmaf(sa, bb.z, s2); s3 = fmaf(sa, bb.w, s3);
;       s0 = fmaf(vv, kp.x, s0); s1 = fmaf(vv, kp.y, s1); s2 = fmaf(vv, kp.z, s2); s3 = fmaf(vv, kp.w, s3);
;       float y = s0 * rr.x + s1 * rr.y + s2 * rr.z + s3 * rr.w;
;       y = allreduce16(y);
;       if (j == s) ykeep = y;
;       om = om_n; kk = kk_n; bb = bb_n; kp = kp_n; rr = rr_n; vv = vv_n;
;     }
	v_pk_mul_f32 v[176:177], v[60:61], v[94:95]
	v_pk_fma_f32 v[176:177], v[58:59], v[96:97], v[176:177]
	ds_read_b128 v[138:141], v78 offset:21760
	ds_read_b128 v[134:137], v78 offset:21504
	v_pk_fma_f32 v[180:181], v[60:61], v[90:91], v[60:61] neg_lo:[1,0,0] neg_hi:[1,0,0]
	v_add_f32_e32 v178, v176, v177
	v_pk_fma_f32 v[182:183], v[58:59], v[92:93], v[58:59] neg_lo:[1,0,0] neg_hi:[1,0,0]
	ds_read_b128 v[152:155], v78 offset:22272
	v_add_f32_dpp v178, v178, v178 quad_perm:[1,0,3,2] row_mask:0xf bank_mask:0xf bound_ctrl:1
	v_pk_fma_f32 v[180:181], v[110:111], v[102:103], v[180:181] op_sel_hi:[0,1,1]
	v_pk_fma_f32 v[182:183], v[110:111], v[104:105], v[182:183] op_sel_hi:[0,1,1]
	v_add_f32_dpp v178, v178, v178 quad_perm:[2,3,0,1] row_mask:0xf bank_mask:0xf bound_ctrl:1
	v_pk_mul_f32 v[184:185], v[60:61], v[156:157]
	v_pk_fma_f32 v[184:185], v[58:59], v[158:159], v[184:185]
	v_add_f32_dpp v178, v178, v178 row_half_mirror row_mask:0xf bank_mask:0xf bound_ctrl:1
	v_add_f32_e32 v171, v184, v185
	ds_read_b32 v146, v79 offset:22784
	v_add_f32_dpp v178, v178, v178 row_mirror row_mask:0xf bank_mask:0xf bound_ctrl:1
	ds_read_b128 v[142:145], v78 offset:22016
	ds_read_b128 v[156:159], v78 offset:22528
	v_pk_fma_f32 v[60:61], v[178:179], v[98:99], v[180:181] op_sel_hi:[0,1,1] neg_lo:[1,0,0] neg_hi:[1,0,0]
	v_pk_fma_f32 v[58:59], v[178:179], v[100:101], v[182:183] op_sel_hi:[0,1,1] neg_lo:[1,0,0] neg_hi:[1,0,0]
	s_waitcnt lgkmcnt(7)
	v_pk_mul_f32 v[176:177], v[60:61], v[116:117]
	v_pk_fma_f32 v[176:177], v[58:59], v[118:119], v[176:177]
	ds_read_b128 v[94:97], v78 offset:23296
	ds_read_b128 v[90:93], v78 offset:23040
	v_pk_fma_f32 v[180:181], v[60:61], v[112:113], v[60:61] neg_lo:[1,0,0] neg_hi:[1,0,0]
	v_add_f32_e32 v178, v176, v177
	v_pk_fma_f32 v[182:183], v[58:59], v[114:115], v[58:59] neg_lo:[1,0,0] neg_hi:[1,0,0]
	ds_read_b128 v[102:105], v78 offset:23808
	v_add_f32_dpp v178, v178, v178 quad_perm:[1,0,3,2] row_mask:0xf bank_mask:0xf bound_ctrl:1
	v_pk_fma_f32 v[180:181], v[132:133], v[124:125], v[180:181] op_sel_hi:[0,1,1]
	v_pk_fma_f32 v[182:183], v[132:133], v[126:127], v[182:183] op_sel_hi:[0,1,1]
	v_add_f32_dpp v178, v178, v178 quad_perm:[2,3,0,1] row_mask:0xf bank_mask:0xf bound_ctrl:1
	v_pk_mul_f32 v[184:185], v[60:61], v[106:107]
	v_pk_fma_f32 v[184:185], v[58:59], v[108:109], v[184:185]
	v_add_f32_dpp v178, v178, v178 row_half_mirror row_mask:0xf bank_mask:0xf bound_ctrl:1
	v_add_f32_e32 v172, v184, v185
	ds_read_b32 v110, v79 offset:24320
	v_add_f32_dpp v178, v178, v178 row_mirror row_mask:0xf bank_mask:0xf bound_ctrl:1
	ds_read_b128 v[98:101], v78 offset:23552
	ds_read_b128 v[106:109], v78 offset:24064
	v_pk_fma_f32 v[60:61], v[178:179], v[120:121], v[180:181] op_sel_hi:[0,1,1] neg_lo:[1,0,0] neg_hi:[1,0,0]
	v_pk_fma_f32 v[58:59], v[178:179], v[122:123], v[182:183] op_sel_hi:[0,1,1] neg_lo:[1,0,0] neg_hi:[1,0,0]
	s_mov_b64 s[12:13], exec
	s_mov_b64 exec, 1
	ds_add_u32 v193, v195 offset:8
	s_mov_b64 exec, s[12:13]
	v_add_u32_e32 v194, 4, v194
	s_waitcnt lgkmcnt(8)
	v_pk_mul_f32 v[176:177], v[60:61], v[138:139]
	v_pk_fma_f32 v[176:177], v[58:59], v[140:141], v[176:177]
	v_pk_fma_f32 v[180:181], v[60:61], v[134:135], v[60:61] neg_lo:[1,0,0] neg_hi:[1,0,0]
	v_add_f32_e32 v178, v176, v177
	v_pk_fma_f32 v[182:183], v[58:59], v[136:137], v[58:59] neg_lo:[1,0,0] neg_hi:[1,0,0]
	s_nop 0
	v_add_f32_dpp v178, v178, v178 quad_perm:[1,0,3,2] row_mask:0xf bank_mask:0xf bound_ctrl:1
	v_pk_fma_f32 v[180:181], v[146:147], v[152:153], v[180:181] op_sel_hi:[0,1,1]
	v_pk_fma_f32 v[182:183], v[146:147], v[154:155], v[182:183] op_sel_hi:[0,1,1]
	v_add_f32_dpp v178, v178, v178 quad_perm:[2,3,0,1] row_mask:0xf bank_mask:0xf bound_ctrl:1
	v_pk_mul_f32 v[184:185], v[60:61], v[128:129]
	v_pk_fma_f32 v[184:185], v[58:59], v[130:131], v[184:185]
	v_add_f32_dpp v178, v178, v178 row_half_mirror row_mask:0xf bank_mask:0xf bound_ctrl:1
	v_add_f32_e32 v173, v184, v185
	s_nop 0
	v_add_f32_dpp v178, v178, v178 row_mirror row_mask:0xf bank_mask:0xf bound_ctrl:1
	v_pk_fma_f32 v[60:61], v[178:179], v[142:143], v[180:181] op_sel_hi:[0,1,1] neg_lo:[1,0,0] neg_hi:[1,0,0]
	v_pk_fma_f32 v[58:59], v[178:179], v[144:145], v[182:183] op_sel_hi:[0,1,1] neg_lo:[1,0,0] neg_hi:[1,0,0]
	s_waitcnt lgkmcnt(2)
; __device__ __forceinline__ bf16_t f2bf(float f) { return (bf16_t)(pack2(f, 0.f) & 0xffffu); }
; __device__ __forceinline__ void rwkv_scan_unit(CP p, int u, char* smem) {
;     ...
;       float y = s0 * rr.x + s1 * rr.y + s2 * rr.z + s3 * rr.w;
;       y = allreduce16(y);
;       if (j == s) ykeep = y;
;       om = om_n; kk = kk_n; bb = bb_n; kp = kp_n; rr = rr_n; vv = vv_n;
;     }
;     Y[(size_t)(rowof(b, c * 16) + j) * 1024 + 256 + h * 64 + rowv] = f2bf(ykeep);
;     if (c + 1 < NCH) lwrite((c + 1) & 1);
;     half_barrier(smem);
	v_pk_mul_f32 v[176:177], v[60:61], v[94:95]
	v_pk_fma_f32 v[176:177], v[58:59], v[96:97], v[176:177]
	v_pk_fma_f32 v[180:181], v[60:61], v[90:91], v[60:61] neg_lo:[1,0,0] neg_hi:[1,0,0]
	v_add_f32_e32 v178, v176, v177
	v_pk_fma_f32 v[182:183], v[58:59], v[92:93], v[58:59] neg_lo:[1,0,0] neg_hi:[1,0,0]
	s_nop 0
	v_add_f32_dpp v178, v178, v178 quad_perm:[1,0,3,2] row_mask:0xf bank_mask:0xf bound_ctrl:1
	v_pk_fma_f32 v[180:181], v[110:111], v[102:103], v[180:181] op_sel_hi:[0,1,1]
	v_pk_fma_f32 v[182:183], v[110:111], v[104:105], v[182:183] op_sel_hi:[0,1,1]
	v_add_f32_dpp v178, v178, v178 quad_perm:[2,3,0,1] row_mask:0xf bank_mask:0xf bound_ctrl:1
	v_pk_mul_f32 v[184:185], v[60:61], v[156:157]
	v_pk_fma_f32 v[184:185], v[58:59], v[158:159], v[184:185]
	v_add_f32_dpp v178, v178, v178 row_half_mirror row_mask:0xf bank_mask:0xf bound_ctrl:1
	v_add_f32_e32 v174, v184, v185
	s_nop 0
	v_add_f32_dpp v178, v178, v178 row_mirror row_mask:0xf bank_mask:0xf bound_ctrl:1
	v_pk_fma_f32 v[60:61], v[178:179], v[98:99], v[180:181] op_sel_hi:[0,1,1] neg_lo:[1,0,0] neg_hi:[1,0,0]
	v_pk_fma_f32 v[58:59], v[178:179], v[100:101], v[182:183] op_sel_hi:[0,1,1] neg_lo:[1,0,0] neg_hi:[1,0,0]
	s_waitcnt lgkmcnt(1)
	v_pk_mul_f32 v[184:185], v[60:61], v[106:107]
	v_pk_fma_f32 v[184:185], v[58:59], v[108:109], v[184:185]
	v_add_f32_e32 v175, v184, v185
	v_add_f32_dpp v160, v160, v160 row_ror:8 row_mask:0xf bank_mask:0x3 bound_ctrl:1
	v_add_f32_dpp v161, v161, v161 row_ror:8 row_mask:0xf bank_mask:0x3 bound_ctrl:1
	v_add_f32_dpp v162, v162, v162 row_ror:8 row_mask:0xf bank_mask:0x3 bound_ctrl:1
	v_add_f32_dpp v163, v163, v163 row_ror:8 row_mask:0xf bank_mask:0x3 bound_ctrl:1
	v_add_f32_dpp v164, v164, v164 row_ror:8 row_mask:0xf bank_mask:0x3 bound_ctrl:1
	v_add_f32_dpp v165, v165, v165 row_ror:8 row_mask:0xf bank_mask:0x3 bound_ctrl:1
	v_add_f32_dpp v166, v166, v166 row_ror:8 row_mask:0xf bank_mask:0x3 bound_ctrl:1
	v_add_f32_dpp v167, v167, v167 row_ror:8 row_mask:0xf bank_mask:0x3 bound_ctrl:1
	v_add_f32_dpp v160, v168, v168 row_ror:8 row_mask:0xf bank_mask:0xc bound_ctrl:1
	v_add_f32_dpp v161, v169, v169 row_ror:8 row_mask:0xf bank_mask:0xc bound_ctrl:1
	v_add_f32_dpp v162, v170, v170 row_ror:8 row_mask:0xf bank_mask:0xc bound_ctrl:1
	v_add_f32_dpp v163, v171, v171 row_ror:8 row_mask:0xf bank_mask:0xc bound_ctrl:1
	v_add_f32_dpp v164, v172, v172 row_ror:8 row_mask:0xf bank_mask:0xc bound_ctrl:1
	v_add_f32_dpp v165, v173, v173 row_ror:8 row_mask:0xf bank_mask:0xc bound_ctrl:1
	v_add_f32_dpp v166, v174, v174 row_ror:8 row_mask:0xf bank_mask:0xc bound_ctrl:1
	v_add_f32_dpp v167, v175, v175 row_ror:8 row_mask:0xf bank_mask:0xc bound_ctrl:1
	v_add_f32_dpp v160, v160, v160 row_half_mirror row_mask:0xf bank_mask:0x5 bound_ctrl:1
	v_add_f32_dpp v161, v161, v161 row_half_mirror row_mask:0xf bank_mask:0x5 bound_ctrl:1
	v_add_f32_dpp v162, v162, v162 row_half_mirror row_mask:0xf bank_mask:0x5 bound_ctrl:1
	v_add_f32_dpp v163, v163, v163 row_half_mirror row_mask:0xf bank_mask:0x5 bound_ctrl:1
	v_add_f32_dpp v160, v164, v164 row_half_mirror row_mask:0xf bank_mask:0xa bound_ctrl:1
	v_add_f32_dpp v161, v165, v165 row_half_mirror row_mask:0xf bank_mask:0xa bound_ctrl:1
	v_add_f32_dpp v162, v166, v166 row_half_mirror row_mask:0xf bank_mask:0xa bound_ctrl:1
	v_add_f32_dpp v163, v167, v167 row_half_mirror row_mask:0xf bank_mask:0xa bound_ctrl:1
	v_and_b32_e32 v186, 2, v76
	v_cmp_ne_u32_e32 vcc, 0, v186
	v_and_b32_e32 v186, 1, v76
	s_nop 0
	v_cndmask_b32_e32 v187, v160, v162, vcc
	v_cndmask_b32_e32 v188, v162, v160, vcc
	v_cndmask_b32_e32 v189, v161, v163, vcc
	v_cndmask_b32_e32 v190, v163, v161, vcc
	v_cmp_ne_u32_e32 vcc, 0, v186
	v_add_f32_dpp v160, v188, v187 quad_perm:[2,3,0,1] row_mask:0xf bank_mask:0xf bound_ctrl:1
	v_add_f32_dpp v161, v190, v189 quad_perm:[2,3,0,1] row_mask:0xf bank_mask:0xf bound_ctrl:1
	v_cndmask_b32_e32 v187, v160, v161, vcc
	v_cndmask_b32_e32 v188, v161, v160, vcc
	s_nop 1
	v_add_f32_dpp v82, v188, v187 quad_perm:[1,0,3,2] row_mask:0xf bank_mask:0xf bound_ctrl:1
	s_lshl_b32 s5, s4, 4
	s_add_i32 s5, s5, s11
	s_cmp_eq_u32 s4, 0
	s_cselect_b32 s5, s10, s5
	v_or_b32_e32 v12, s5, v76
	v_ashrrev_i32_e32 v13, 31, v12
	v_lshlrev_b64 v[12:13], 11, v[12:13]
	v_cvt_pk_bf16_f32 v14, v82, s0
	v_lshl_add_u64 v[12:13], v[56:57], 0, v[12:13]
	global_store_short v[12:13], v14, off
	s_waitcnt lgkmcnt(0)
